# gen6 with static priority on waves 0-3: PV and row-sum MFMAs in the non-scaled f8f6f4 form (unit scales), merged LDS waits
# speedup vs baseline: 1.1740x; 1.0125x over previous
; template <bool FUSE>
; DEVINL void qkt(f32x16& p0, f32x16& p1, const char* Ks, const i32x8* q8, int r32, int hi, f32x16& e1) {
;   p0 = f32x16{}; p1 = f32x16{};
;   const char* ka = Ks + hi * 1024 + r32 * 16; const char* kb = Ks + 4096 + hi * 512 + r32 * 8;
;   const char* ra = Ks + 6144 + hi * 1024 + r32 * 16; const char* rb = Ks + 6144 + 2048 + hi * 512 + r32 * 8;
;   u32x4 fa[3][2]; u32x2 fb[3][2];
;     ...
;   QK_LD(0, 0);
; #pragma unroll
;   for (int t = 0; t < 3; ++t) {
;     if (t + 1 < 3) QK_LD(t + 1, (t + 1) % 3);
;     const i32x8 a0 = mk6((int)fa[t][0][0], (int)fa[t][0][1], (int)fa[t][0][2], (int)fa[t][0][3], (int)fb[t][0][0], (int)fb[t][0][1]);
;     const i32x8 a1 = mk6((int)fa[t][1][0], (int)fa[t][1][1], (int)fa[t][1][2], (int)fa[t][1][3], (int)fb[t][1][0], (int)fb[t][1][1]);
;     p0 = MFMA6(a0, q8[t], p0);
;     if (FUSE) {
; #pragma unroll
;       for (int r = 0; r < 3; ++r) { const int rr = t * 6 + r; if (rr < 16) e1[rr] = __builtin_amdgcn_exp2f(e1[rr]); }
;     }
;     p1 = MFMA6(a1, q8[t], p1);
;     if (FUSE) {
; #pragma unroll
;       for (int r = 3; r < 6; ++r) { const int rr = t * 6 + r; if (rr < 16) e1[rr] = __builtin_amdgcn_exp2f(e1[rr]); }
;     }
;     SBAR();
;   }
; DEVINL void pv_psm(f32x16* o, const VFrag& f, const i32x8& pa, f32x16& lsum, const i32x8& ones8,
;                    f32x16& p0, f32x16& p1, float& m_reg, float& mn, float& alpha, int kvalid, int hi) {
;   constexpr float C = MLA_SCALE * 1.4426950408889634f;
;     ...
;   if (kvalid < 64) {
; #pragma unroll
;     for (int r = 0; r < 16; ++r) { if (crow(r, hi) >= kvalid) p0[r] = -1e30f; if (32 + crow(r, hi) >= kvalid) p1[r] = -1e30f; }
;   }
;   PVM(0);
;   float pmax = p0[0];
; #pragma unroll
;   for (int r = 1; r < 16; ++r) pmax = fmaxf(pmax, p0[r]);
;   SBAR();
;   PVM(1);
; #pragma unroll
;   for (int r = 0; r < 16; ++r) pmax = fmaxf(pmax, p1[r]);
;   { auto rr = __builtin_amdgcn_permlane32_swap(__float_as_uint(pmax), __float_as_uint(pmax), false, false);
;     pmax = fmaxf(__uint_as_float(rr[0]), __uint_as_float(rr[1])); }
;   SBAR();
;   PVM(2);
;   if (__builtin_expect(__all(pmax - m_reg <= THR / MLA_SCALE), 1)) { mn = m_reg; alpha = 1.f; }
;   else { mn = fmaxf(m_reg, pmax); alpha = __builtin_amdgcn_exp2f((m_reg - mn) * C); m_reg = mn; }
;   const float mnC = PSHIFT - mn * C;
;   const f32x2 C2 = {C, C}, M2 = {mnC, mnC};
; #pragma unroll
.Ldma_done:
	v_exp_f32_e32 v80, v80
	v_exp_f32_e32 v81, v81
	s_waitcnt lgkmcnt(0)
	v_mfma_scale_f32_32x32x64_f8f6f4 v[182:197], v[104:109], v[120:125], v[240:255], v162, v143 op_sel_hi:[0,0,0] cbsz:2 blgp:2
	v_exp_f32_e32 v82, v82
	v_exp_f32_e32 v83, v83
	v_exp_f32_e32 v84, v84
	v_exp_f32_e32 v85, v85
	v_mfma_scale_f32_32x32x64_f8f6f4 v[198:213], v[110:115], v[120:125], v[240:255], v162, v143 op_sel_hi:[0,0,0] cbsz:2 blgp:2
	ds_read_b128 v[104:107], v140 offset:4096
	ds_read_b128 v[108:111], v140 offset:4608
	ds_read_b128 v[112:115], v140 offset:6144
	ds_read_b128 v[116:119], v140 offset:6656
	v_exp_f32_e32 v86, v86
	v_mfma_scale_f32_32x32x64_f8f6f4 v[182:197], v[148:153], v[126:131], v[182:197], v162, v143 op_sel_hi:[0,0,0] cbsz:2 blgp:2
	v_exp_f32_e32 v87, v87
	v_exp_f32_e32 v88, v88
	v_exp_f32_e32 v89, v89
	v_exp_f32_e32 v90, v90
	v_mfma_scale_f32_32x32x64_f8f6f4 v[198:213], v[154:159], v[126:131], v[198:213], v162, v143 op_sel_hi:[0,0,0] cbsz:2 blgp:2
	ds_read_b128 v[148:151], v140 offset:8192
	ds_read_b128 v[152:155], v140 offset:8704
	v_exp_f32_e32 v91, v91
	v_exp_f32_e32 v92, v92
	v_mfma_scale_f32_32x32x64_f8f6f4 v[182:197], v[214:219], v[132:137], v[182:197], v162, v143 op_sel_hi:[0,0,0] cbsz:2 blgp:2
	v_exp_f32_e32 v93, v93
	v_exp_f32_e32 v94, v94
	v_exp_f32_e32 v95, v95
	v_cvt_pk_fp8_f32 v96, v64, v65
	v_cvt_pk_fp8_f32 v97, v68, v69
	v_mfma_scale_f32_32x32x64_f8f6f4 v[198:213], v[220:225], v[132:137], v[198:213], v162, v143 op_sel_hi:[0,0,0] cbsz:2 blgp:2
	ds_read_b128 v[214:217], v140 offset:10240
	ds_read_b128 v[218:221], v140 offset:10752
	v_cvt_pk_fp8_f32 v98, v72, v73
	v_cvt_pk_fp8_f32 v99, v76, v77
	v_cvt_pk_fp8_f32 v96, v66, v67 op_sel:[0,0,1]
	v_cvt_pk_fp8_f32 v97, v70, v71 op_sel:[0,0,1]
	v_cvt_pk_fp8_f32 v98, v74, v75 op_sel:[0,0,1]
	v_cvt_pk_fp8_f32 v99, v78, v79 op_sel:[0,0,1]
	v_cvt_pk_fp8_f32 v100, v80, v81
	v_cvt_pk_fp8_f32 v101, v84, v85
	v_cvt_pk_fp8_f32 v102, v88, v89
	v_cvt_pk_fp8_f32 v103, v92, v93
	v_cvt_pk_fp8_f32 v100, v82, v83 op_sel:[0,0,1]
	v_cvt_pk_fp8_f32 v101, v86, v87 op_sel:[0,0,1]
	v_cvt_pk_fp8_f32 v102, v90, v91 op_sel:[0,0,1]
	v_cvt_pk_fp8_f32 v103, v94, v95 op_sel:[0,0,1]
	s_waitcnt lgkmcnt(2)
	s_nop 0
	v_mfma_f32_32x32x64_f8f6f4 v[0:15], v[96:103], v[104:111], v[0:15]
	v_max_f32_e32 v229, v182, v183
	v_max3_f32 v229, v229, v184, v185
	v_max3_f32 v229, v229, v186, v187
	v_max3_f32 v229, v229, v188, v189
	v_max3_f32 v229, v229, v190, v191
	v_max3_f32 v229, v229, v192, v193
	v_max3_f32 v229, v229, v194, v195
	v_max3_f32 v229, v229, v196, v197
	v_mfma_f32_32x32x64_f8f6f4 v[48:63], v[96:103], v[112:119], v[48:63]
	v_max3_f32 v229, v229, v198, v199
	v_max3_f32 v229, v229, v200, v201
	v_max3_f32 v229, v229, v202, v203
	v_max3_f32 v229, v229, v204, v205
	v_max3_f32 v229, v229, v206, v207
	v_max3_f32 v229, v229, v208, v209
	v_max3_f32 v229, v229, v210, v211
	v_max3_f32 v229, v229, v212, v213
	v_mov_b32_e32 v160, v229
	s_nop 1
	v_permlane32_swap_b32_e32 v229, v160
	v_max_f32_e32 v229, v229, v160
	v_cmp_ge_f32_e32 vcc, s69, v229
	s_cmp_eq_u64 vcc, exec
	v_mov_b32_e32 v226, 1.0
	s_cbranch_scc0 .Lslow_a0
	v_mfma_f32_32x32x64_f8f6f4 v[16:31], v[96:103], v[148:155], v[16:31]
	v_exp_f32_e32 v182, v182
	v_exp_f32_e32 v183, v183
	v_exp_f32_e32 v184, v184
	v_exp_f32_e32 v185, v185
	v_exp_f32_e32 v186, v186
	v_exp_f32_e32 v187, v187
	s_waitcnt lgkmcnt(0)
	v_mfma_f32_32x32x64_f8f6f4 v[32:47], v[96:103], v[214:221], v[32:47]
	v_exp_f32_e32 v188, v188
	v_exp_f32_e32 v189, v189
	v_exp_f32_e32 v190, v190
	v_exp_f32_e32 v191, v191
	v_exp_f32_e32 v192, v192
	v_exp_f32_e32 v193, v193
	v_mfma_f32_16x16x128_f8f6f4 v[144:147], v[232:239], v[96:103], 0
	v_exp_f32_e32 v194, v194
	v_exp_f32_e32 v195, v195
	v_exp_f32_e32 v196, v196
	v_exp_f32_e32 v197, v197
; template <bool FUSE>
; DEVINL void qkt(f32x16& p0, f32x16& p1, const char* Ks, const i32x8* q8, int r32, int hi, f32x16& e1) {
;   p0 = f32x16{}; p1 = f32x16{};
;   const char* ka = Ks + hi * 1024 + r32 * 16; const char* kb = Ks + 4096 + hi * 512 + r32 * 8;
;   const char* ra = Ks + 6144 + hi * 1024 + r32 * 16; const char* rb = Ks + 6144 + 2048 + hi * 512 + r32 * 8;
;   u32x4 fa[3][2]; u32x2 fb[3][2];
;     ...
;   QK_LD(0, 0);
; #pragma unroll
;   for (int t = 0; t < 3; ++t) {
;     if (t + 1 < 3) QK_LD(t + 1, (t + 1) % 3);
;     const i32x8 a0 = mk6((int)fa[t][0][0], (int)fa[t][0][1], (int)fa[t][0][2], (int)fa[t][0][3], (int)fb[t][0][0], (int)fb[t][0][1]);
;     const i32x8 a1 = mk6((int)fa[t][1][0], (int)fa[t][1][1], (int)fa[t][1][2], (int)fa[t][1][3], (int)fb[t][1][0], (int)fb[t][1][1]);
;     p0 = MFMA6(a0, q8[t], p0);
;     if (FUSE) {
; #pragma unroll
;       for (int r = 0; r < 3; ++r) { const int rr = t * 6 + r; if (rr < 16) e1[rr] = __builtin_amdgcn_exp2f(e1[rr]); }
;     }
;     p1 = MFMA6(a1, q8[t], p1);
;     if (FUSE) {
; #pragma unroll
;       for (int r = 3; r < 6; ++r) { const int rr = t * 6 + r; if (rr < 16) e1[rr] = __builtin_amdgcn_exp2f(e1[rr]); }
;     }
;     SBAR();
;   }
; DEVINL void pv_psm(f32x16* o, const VFrag& f, const i32x8& pa, f32x16& lsum, const i32x8& ones8,
;                    f32x16& p0, f32x16& p1, float& m_reg, float& mn, float& alpha, int kvalid, int hi) {
;   constexpr float C = MLA_SCALE * 1.4426950408889634f;
;     ...
;   if (kvalid < 64) {
; #pragma unroll
;     for (int r = 0; r < 16; ++r) { if (crow(r, hi) >= kvalid) p0[r] = -1e30f; if (32 + crow(r, hi) >= kvalid) p1[r] = -1e30f; }
;   }
;   PVM(0);
;   float pmax = p0[0];
; #pragma unroll
;   for (int r = 1; r < 16; ++r) pmax = fmaxf(pmax, p0[r]);
;   SBAR();
;   PVM(1);
; #pragma unroll
;   for (int r = 0; r < 16; ++r) pmax = fmaxf(pmax, p1[r]);
;   { auto rr = __builtin_amdgcn_permlane32_swap(__float_as_uint(pmax), __float_as_uint(pmax), false, false);
;     pmax = fmaxf(__uint_as_float(rr[0]), __uint_as_float(rr[1])); }
;   SBAR();
;   PVM(2);
;   if (__builtin_expect(__all(pmax - m_reg <= THR / MLA_SCALE), 1)) { mn = m_reg; alpha = 1.f; }
;   else { mn = fmaxf(m_reg, pmax); alpha = __builtin_amdgcn_exp2f((m_reg - mn) * C); m_reg = mn; }
;   const float mnC = PSHIFT - mn * C;
;   const f32x2 C2 = {C, C}, M2 = {mnC, mnC};
; #pragma unroll
.Ljoin_a0:
	ds_read_b128 v[104:107], v173 offset:18432
	ds_read_b64 v[108:109], v176 offset:18432
	ds_read_b128 v[110:113], v173 offset:18944
	ds_read_b64 v[114:115], v176 offset:18688
	ds_read_b128 v[148:151], v173 offset:20480
	ds_read_b64 v[152:153], v176 offset:19456
	ds_read_b128 v[154:157], v173 offset:20992
	ds_read_b64 v[158:159], v176 offset:19712
	ds_read_b128 v[214:217], v173 offset:24576
	ds_read_b64 v[218:219], v176 offset:22528
	ds_read_b128 v[220:223], v173 offset:25088
	ds_read_b64 v[224:225], v176 offset:22784
	v_fma_f32 v180, v179, v180, v144
	v_exp_f32_e32 v198, v198
	v_exp_f32_e32 v199, v199
	s_waitcnt lgkmcnt(0)
	v_mfma_scale_f32_32x32x64_f8f6f4 v[64:79], v[104:109], v[120:125], v[240:255], v162, v143 op_sel_hi:[0,0,0] cbsz:2 blgp:2
	v_exp_f32_e32 v200, v200
	v_exp_f32_e32 v201, v201
	v_exp_f32_e32 v202, v202
	v_exp_f32_e32 v203, v203
	v_mfma_scale_f32_32x32x64_f8f6f4 v[80:95], v[110:115], v[120:125], v[240:255], v162, v143 op_sel_hi:[0,0,0] cbsz:2 blgp:2
	ds_read_b128 v[104:107], v140 offset:12288
	ds_read_b128 v[108:111], v140 offset:12800
	ds_read_b128 v[112:115], v140 offset:14336
	ds_read_b128 v[116:119], v140 offset:14848
	v_exp_f32_e32 v204, v204
	v_mfma_scale_f32_32x32x64_f8f6f4 v[64:79], v[148:153], v[126:131], v[64:79], v162, v143 op_sel_hi:[0,0,0] cbsz:2 blgp:2
	v_exp_f32_e32 v205, v205
	v_exp_f32_e32 v206, v206
	v_exp_f32_e32 v207, v207
	v_exp_f32_e32 v208, v208
	v_mfma_scale_f32_32x32x64_f8f6f4 v[80:95], v[154:159], v[126:131], v[80:95], v162, v143 op_sel_hi:[0,0,0] cbsz:2 blgp:2
	ds_read_b128 v[148:151], v140 offset:16384
	ds_read_b128 v[152:155], v140 offset:16896
	v_exp_f32_e32 v209, v209
	v_exp_f32_e32 v210, v210
	v_mfma_scale_f32_32x32x64_f8f6f4 v[64:79], v[214:219], v[132:137], v[64:79], v162, v143 op_sel_hi:[0,0,0] cbsz:2 blgp:2
	v_exp_f32_e32 v211, v211
	v_exp_f32_e32 v212, v212
	v_exp_f32_e32 v213, v213
	v_cvt_pk_fp8_f32 v96, v182, v183
	v_cvt_pk_fp8_f32 v97, v186, v187
	v_mfma_scale_f32_32x32x64_f8f6f4 v[80:95], v[220:225], v[132:137], v[80:95], v162, v143 op_sel_hi:[0,0,0] cbsz:2 blgp:2
	ds_read_b128 v[214:217], v140 offset:18432
	ds_read_b128 v[218:221], v140 offset:18944
	v_cvt_pk_fp8_f32 v98, v190, v191
	v_cvt_pk_fp8_f32 v99, v194, v195
	v_cvt_pk_fp8_f32 v96, v184, v185 op_sel:[0,0,1]
	v_cvt_pk_fp8_f32 v97, v188, v189 op_sel:[0,0,1]
	v_cvt_pk_fp8_f32 v98, v192, v193 op_sel:[0,0,1]
	v_cvt_pk_fp8_f32 v99, v196, v197 op_sel:[0,0,1]
	v_cvt_pk_fp8_f32 v100, v198, v199
	v_cvt_pk_fp8_f32 v101, v202, v203
	v_cvt_pk_fp8_f32 v102, v206, v207
	v_cvt_pk_fp8_f32 v103, v210, v211
	v_cvt_pk_fp8_f32 v100, v200, v201 op_sel:[0,0,1]
	v_cvt_pk_fp8_f32 v101, v204, v205 op_sel:[0,0,1]
	v_cvt_pk_fp8_f32 v102, v208, v209 op_sel:[0,0,1]
	v_cvt_pk_fp8_f32 v103, v212, v213 op_sel:[0,0,1]
	s_waitcnt lgkmcnt(2)
	s_nop 0
	v_mfma_f32_32x32x64_f8f6f4 v[0:15], v[96:103], v[104:111], v[0:15]
	v_max_f32_e32 v229, v64, v65
	v_max3_f32 v229, v229, v66, v67
	v_max3_f32 v229, v229, v68, v69
	v_max3_f32 v229, v229, v70, v71
	v_max3_f32 v229, v229, v72, v73
	v_max3_f32 v229, v229, v74, v75
	v_max3_f32 v229, v229, v76, v77
	v_max3_f32 v229, v229, v78, v79
	v_mfma_f32_32x32x64_f8f6f4 v[48:63], v[96:103], v[112:119], v[48:63]
	v_max3_f32 v229, v229, v80, v81
	v_max3_f32 v229, v229, v82, v83
	v_max3_f32 v229, v229, v84, v85
	v_max3_f32 v229, v229, v86, v87
	v_max3_f32 v229, v229, v88, v89
	v_max3_f32 v229, v229, v90, v91
	v_max3_f32 v229, v229, v92, v93
	v_max3_f32 v229, v229, v94, v95
	v_mov_b32_e32 v160, v229
	s_nop 1
	v_permlane32_swap_b32_e32 v229, v160
	v_max_f32_e32 v229, v229, v160
	v_cmp_ge_f32_e32 vcc, s69, v229
	s_cmp_eq_u64 vcc, exec
	v_mov_b32_e32 v228, 1.0
	s_cbranch_scc0 .Lslow_b0
	v_mfma_f32_32x32x64_f8f6f4 v[16:31], v[96:103], v[148:155], v[16:31]
	v_exp_f32_e32 v64, v64
	v_exp_f32_e32 v65, v65
	v_exp_f32_e32 v66, v66
	v_exp_f32_e32 v67, v67
	v_exp_f32_e32 v68, v68
	v_exp_f32_e32 v69, v69
	s_waitcnt lgkmcnt(0)
	v_mfma_f32_32x32x64_f8f6f4 v[32:47], v[96:103], v[214:221], v[32:47]
	v_exp_f32_e32 v70, v70
	v_exp_f32_e32 v71, v71
	v_exp_f32_e32 v72, v72
	v_exp_f32_e32 v73, v73
	v_exp_f32_e32 v74, v74
	v_exp_f32_e32 v75, v75
	v_mfma_f32_16x16x128_f8f6f4 v[144:147], v[232:239], v[96:103], 0
	v_exp_f32_e32 v76, v76
	v_exp_f32_e32 v77, v77
	v_exp_f32_e32 v78, v78
	v_exp_f32_e32 v79, v79
	s_waitcnt vmcnt(0)
	s_barrier

; template <bool FUSE>
; DEVINL void qkt(f32x16& p0, f32x16& p1, const char* Ks, const i32x8* q8, int r32, int hi, f32x16& e1) {
;   p0 = f32x16{}; p1 = f32x16{};
;   const char* ka = Ks + hi * 1024 + r32 * 16; const char* kb = Ks + 4096 + hi * 512 + r32 * 8;
;   const char* ra = Ks + 6144 + hi * 1024 + r32 * 16; const char* rb = Ks + 6144 + 2048 + hi * 512 + r32 * 8;
;   u32x4 fa[3][2]; u32x2 fb[3][2];
;     ...
;   QK_LD(0, 0);
; #pragma unroll
;   for (int t = 0; t < 3; ++t) {
;     if (t + 1 < 3) QK_LD(t + 1, (t + 1) % 3);
;     const i32x8 a0 = mk6((int)fa[t][0][0], (int)fa[t][0][1], (int)fa[t][0][2], (int)fa[t][0][3], (int)fb[t][0][0], (int)fb[t][0][1]);
;     const i32x8 a1 = mk6((int)fa[t][1][0], (int)fa[t][1][1], (int)fa[t][1][2], (int)fa[t][1][3], (int)fb[t][1][0], (int)fb[t][1][1]);
;     p0 = MFMA6(a0, q8[t], p0);
;     if (FUSE) {
; #pragma unroll
;       for (int r = 0; r < 3; ++r) { const int rr = t * 6 + r; if (rr < 16) e1[rr] = __builtin_amdgcn_exp2f(e1[rr]); }
;     }
;     p1 = MFMA6(a1, q8[t], p1);
;     if (FUSE) {
; #pragma unroll
;       for (int r = 3; r < 6; ++r) { const int rr = t * 6 + r; if (rr < 16) e1[rr] = __builtin_amdgcn_exp2f(e1[rr]); }
;     }
;     SBAR();
;   }
; DEVINL void pv_psm(f32x16* o, const VFrag& f, const i32x8& pa, f32x16& lsum, const i32x8& ones8,
;                    f32x16& p0, f32x16& p1, float& m_reg, float& mn, float& alpha, int kvalid, int hi) {
;   constexpr float C = MLA_SCALE * 1.4426950408889634f;
;     ...
;   if (kvalid < 64) {
; #pragma unroll
;     for (int r = 0; r < 16; ++r) { if (crow(r, hi) >= kvalid) p0[r] = -1e30f; if (32 + crow(r, hi) >= kvalid) p1[r] = -1e30f; }
;   }
;   PVM(0);
;   float pmax = p0[0];
; #pragma unroll
;   for (int r = 1; r < 16; ++r) pmax = fmaxf(pmax, p0[r]);
;   SBAR();
;   PVM(1);
; #pragma unroll
;   for (int r = 0; r < 16; ++r) pmax = fmaxf(pmax, p1[r]);
;   { auto rr = __builtin_amdgcn_permlane32_swap(__float_as_uint(pmax), __float_as_uint(pmax), false, false);
;     pmax = fmaxf(__uint_as_float(rr[0]), __uint_as_float(rr[1])); }
;   SBAR();
;   PVM(2);
;   if (__builtin_expect(__all(pmax - m_reg <= THR / MLA_SCALE), 1)) { mn = m_reg; alpha = 1.f; }
;   else { mn = fmaxf(m_reg, pmax); alpha = __builtin_amdgcn_exp2f((m_reg - mn) * C); m_reg = mn; }
;   const float mnC = PSHIFT - mn * C;
;   const f32x2 C2 = {C, C}, M2 = {mnC, mnC};
; #pragma unroll
.Lu1_dma_done:
	v_exp_f32_e32 v80, v80
	v_exp_f32_e32 v81, v81
	s_waitcnt lgkmcnt(0)
	v_mfma_scale_f32_32x32x64_f8f6f4 v[182:197], v[104:109], v[120:125], v[240:255], v162, v143 op_sel_hi:[0,0,0] cbsz:2 blgp:2
	v_exp_f32_e32 v82, v82
	v_exp_f32_e32 v83, v83
	v_exp_f32_e32 v84, v84
	v_exp_f32_e32 v85, v85
	v_mfma_scale_f32_32x32x64_f8f6f4 v[198:213], v[110:115], v[120:125], v[240:255], v162, v143 op_sel_hi:[0,0,0] cbsz:2 blgp:2
	ds_read_b128 v[104:107], v140 offset:20480
	ds_read_b128 v[108:111], v140 offset:20992
	ds_read_b128 v[112:115], v140 offset:22528
	ds_read_b128 v[116:119], v140 offset:23040
	v_exp_f32_e32 v86, v86
	v_mfma_scale_f32_32x32x64_f8f6f4 v[182:197], v[148:153], v[126:131], v[182:197], v162, v143 op_sel_hi:[0,0,0] cbsz:2 blgp:2
	v_exp_f32_e32 v87, v87
	v_exp_f32_e32 v88, v88
	v_exp_f32_e32 v89, v89
	v_exp_f32_e32 v90, v90
	v_mfma_scale_f32_32x32x64_f8f6f4 v[198:213], v[154:159], v[126:131], v[198:213], v162, v143 op_sel_hi:[0,0,0] cbsz:2 blgp:2
	ds_read_b128 v[148:151], v140 offset:24576
	ds_read_b128 v[152:155], v140 offset:25088
	v_exp_f32_e32 v91, v91
	v_exp_f32_e32 v92, v92
	v_mfma_scale_f32_32x32x64_f8f6f4 v[182:197], v[214:219], v[132:137], v[182:197], v162, v143 op_sel_hi:[0,0,0] cbsz:2 blgp:2
	v_exp_f32_e32 v93, v93
	v_exp_f32_e32 v94, v94
	v_exp_f32_e32 v95, v95
	v_cvt_pk_fp8_f32 v96, v64, v65
	v_cvt_pk_fp8_f32 v97, v68, v69
	v_mfma_scale_f32_32x32x64_f8f6f4 v[198:213], v[220:225], v[132:137], v[198:213], v162, v143 op_sel_hi:[0,0,0] cbsz:2 blgp:2
	ds_read_b128 v[214:217], v140 offset:26624
	ds_read_b128 v[218:221], v140 offset:27136
	v_cvt_pk_fp8_f32 v98, v72, v73
	v_cvt_pk_fp8_f32 v99, v76, v77
	v_cvt_pk_fp8_f32 v96, v66, v67 op_sel:[0,0,1]
	v_cvt_pk_fp8_f32 v97, v70, v71 op_sel:[0,0,1]
	v_cvt_pk_fp8_f32 v98, v74, v75 op_sel:[0,0,1]
	v_cvt_pk_fp8_f32 v99, v78, v79 op_sel:[0,0,1]
	v_cvt_pk_fp8_f32 v100, v80, v81
	v_cvt_pk_fp8_f32 v101, v84, v85
	v_cvt_pk_fp8_f32 v102, v88, v89
	v_cvt_pk_fp8_f32 v103, v92, v93
	v_cvt_pk_fp8_f32 v100, v82, v83 op_sel:[0,0,1]
	v_cvt_pk_fp8_f32 v101, v86, v87 op_sel:[0,0,1]
	v_cvt_pk_fp8_f32 v102, v90, v91 op_sel:[0,0,1]
	v_cvt_pk_fp8_f32 v103, v94, v95 op_sel:[0,0,1]
	s_waitcnt lgkmcnt(2)
	s_nop 0
	v_mfma_f32_32x32x64_f8f6f4 v[0:15], v[96:103], v[104:111], v[0:15]
	v_max_f32_e32 v229, v182, v183
	v_max3_f32 v229, v229, v184, v185
	v_max3_f32 v229, v229, v186, v187
	v_max3_f32 v229, v229, v188, v189
	v_max3_f32 v229, v229, v190, v191
	v_max3_f32 v229, v229, v192, v193
	v_max3_f32 v229, v229, v194, v195
	v_max3_f32 v229, v229, v196, v197
	v_mfma_f32_32x32x64_f8f6f4 v[48:63], v[96:103], v[112:119], v[48:63]
	v_max3_f32 v229, v229, v198, v199
	v_max3_f32 v229, v229, v200, v201
	v_max3_f32 v229, v229, v202, v203
	v_max3_f32 v229, v229, v204, v205
	v_max3_f32 v229, v229, v206, v207
	v_max3_f32 v229, v229, v208, v209
	v_max3_f32 v229, v229, v210, v211
	v_max3_f32 v229, v229, v212, v213
	v_mov_b32_e32 v160, v229
	s_nop 1
	v_permlane32_swap_b32_e32 v229, v160
	v_max_f32_e32 v229, v229, v160
	v_cmp_ge_f32_e32 vcc, s69, v229
	s_cmp_eq_u64 vcc, exec
	v_mov_b32_e32 v226, 1.0
	s_cbranch_scc0 .Lslow_a1
	v_mfma_f32_32x32x64_f8f6f4 v[16:31], v[96:103], v[148:155], v[16:31]
	v_exp_f32_e32 v182, v182
	v_exp_f32_e32 v183, v183
	v_exp_f32_e32 v184, v184
	v_exp_f32_e32 v185, v185
	v_exp_f32_e32 v186, v186
	v_exp_f32_e32 v187, v187
	s_waitcnt lgkmcnt(0)
	v_mfma_f32_32x32x64_f8f6f4 v[32:47], v[96:103], v[214:221], v[32:47]
	v_exp_f32_e32 v188, v188
	v_exp_f32_e32 v189, v189
	v_exp_f32_e32 v190, v190
	v_exp_f32_e32 v191, v191
	v_exp_f32_e32 v192, v192
	v_exp_f32_e32 v193, v193
	v_mfma_f32_16x16x128_f8f6f4 v[144:147], v[232:239], v[96:103], 0
	v_exp_f32_e32 v194, v194
	v_exp_f32_e32 v195, v195
	v_exp_f32_e32 v196, v196
	v_exp_f32_e32 v197, v197
; template <bool FUSE>
; DEVINL void qkt(f32x16& p0, f32x16& p1, const char* Ks, const i32x8* q8, int r32, int hi, f32x16& e1) {
;   p0 = f32x16{}; p1 = f32x16{};
;   const char* ka = Ks + hi * 1024 + r32 * 16; const char* kb = Ks + 4096 + hi * 512 + r32 * 8;
;   const char* ra = Ks + 6144 + hi * 1024 + r32 * 16; const char* rb = Ks + 6144 + 2048 + hi * 512 + r32 * 8;
;   u32x4 fa[3][2]; u32x2 fb[3][2];
;     ...
;   QK_LD(0, 0);
; #pragma unroll
;   for (int t = 0; t < 3; ++t) {
;     if (t + 1 < 3) QK_LD(t + 1, (t + 1) % 3);
;     const i32x8 a0 = mk6((int)fa[t][0][0], (int)fa[t][0][1], (int)fa[t][0][2], (int)fa[t][0][3], (int)fb[t][0][0], (int)fb[t][0][1]);
;     const i32x8 a1 = mk6((int)fa[t][1][0], (int)fa[t][1][1], (int)fa[t][1][2], (int)fa[t][1][3], (int)fb[t][1][0], (int)fb[t][1][1]);
;     p0 = MFMA6(a0, q8[t], p0);
;     if (FUSE) {
; #pragma unroll
;       for (int r = 0; r < 3; ++r) { const int rr = t * 6 + r; if (rr < 16) e1[rr] = __builtin_amdgcn_exp2f(e1[rr]); }
;     }
;     p1 = MFMA6(a1, q8[t], p1);
;     if (FUSE) {
; #pragma unroll
;       for (int r = 3; r < 6; ++r) { const int rr = t * 6 + r; if (rr < 16) e1[rr] = __builtin_amdgcn_exp2f(e1[rr]); }
;     }
;     SBAR();
;   }
; DEVINL void pv_psm(f32x16* o, const VFrag& f, const i32x8& pa, f32x16& lsum, const i32x8& ones8,
;                    f32x16& p0, f32x16& p1, float& m_reg, float& mn, float& alpha, int kvalid, int hi) {
;   constexpr float C = MLA_SCALE * 1.4426950408889634f;
;     ...
;   if (kvalid < 64) {
; #pragma unroll
;     for (int r = 0; r < 16; ++r) { if (crow(r, hi) >= kvalid) p0[r] = -1e30f; if (32 + crow(r, hi) >= kvalid) p1[r] = -1e30f; }
;   }
;   PVM(0);
;   float pmax = p0[0];
; #pragma unroll
;   for (int r = 1; r < 16; ++r) pmax = fmaxf(pmax, p0[r]);
;   SBAR();
;   PVM(1);
; #pragma unroll
;   for (int r = 0; r < 16; ++r) pmax = fmaxf(pmax, p1[r]);
;   { auto rr = __builtin_amdgcn_permlane32_swap(__float_as_uint(pmax), __float_as_uint(pmax), false, false);
;     pmax = fmaxf(__uint_as_float(rr[0]), __uint_as_float(rr[1])); }
;   SBAR();
;   PVM(2);
;   if (__builtin_expect(__all(pmax - m_reg <= THR / MLA_SCALE), 1)) { mn = m_reg; alpha = 1.f; }
;   else { mn = fmaxf(m_reg, pmax); alpha = __builtin_amdgcn_exp2f((m_reg - mn) * C); m_reg = mn; }
;   const float mnC = PSHIFT - mn * C;
;   const f32x2 C2 = {C, C}, M2 = {mnC, mnC};
; #pragma unroll
.Ljoin_a1:
	ds_read_b128 v[104:107], v173 offset:0
	ds_read_b64 v[108:109], v176 offset:0
	ds_read_b128 v[110:113], v173 offset:512
	ds_read_b64 v[114:115], v176 offset:256
	ds_read_b128 v[148:151], v173 offset:2048
	ds_read_b64 v[152:153], v176 offset:1024
	ds_read_b128 v[154:157], v173 offset:2560
	ds_read_b64 v[158:159], v176 offset:1280
	ds_read_b128 v[214:217], v173 offset:6144
	ds_read_b64 v[218:219], v176 offset:4096
	ds_read_b128 v[220:223], v173 offset:6656
	ds_read_b64 v[224:225], v176 offset:4352
	v_fma_f32 v180, v179, v180, v144
	v_exp_f32_e32 v198, v198
	v_exp_f32_e32 v199, v199
	s_waitcnt lgkmcnt(0)
	v_mfma_scale_f32_32x32x64_f8f6f4 v[64:79], v[104:109], v[120:125], v[240:255], v162, v143 op_sel_hi:[0,0,0] cbsz:2 blgp:2
	v_exp_f32_e32 v200, v200
	v_exp_f32_e32 v201, v201
	v_exp_f32_e32 v202, v202
	v_exp_f32_e32 v203, v203
	v_mfma_scale_f32_32x32x64_f8f6f4 v[80:95], v[110:115], v[120:125], v[240:255], v162, v143 op_sel_hi:[0,0,0] cbsz:2 blgp:2
	ds_read_b128 v[104:107], v140 offset:28672
	ds_read_b128 v[108:111], v140 offset:29184
	ds_read_b128 v[112:115], v140 offset:30720
	ds_read_b128 v[116:119], v140 offset:31232
	v_exp_f32_e32 v204, v204
	v_mfma_scale_f32_32x32x64_f8f6f4 v[64:79], v[148:153], v[126:131], v[64:79], v162, v143 op_sel_hi:[0,0,0] cbsz:2 blgp:2
	v_exp_f32_e32 v205, v205
	v_exp_f32_e32 v206, v206
	v_exp_f32_e32 v207, v207
	v_exp_f32_e32 v208, v208
	v_mfma_scale_f32_32x32x64_f8f6f4 v[80:95], v[154:159], v[126:131], v[80:95], v162, v143 op_sel_hi:[0,0,0] cbsz:2 blgp:2
	ds_read_b128 v[148:151], v140 offset:32768
	ds_read_b128 v[152:155], v140 offset:33280
	v_exp_f32_e32 v209, v209
	v_exp_f32_e32 v210, v210
	v_mfma_scale_f32_32x32x64_f8f6f4 v[64:79], v[214:219], v[132:137], v[64:79], v162, v143 op_sel_hi:[0,0,0] cbsz:2 blgp:2
	v_exp_f32_e32 v211, v211
	v_exp_f32_e32 v212, v212
	v_exp_f32_e32 v213, v213
	v_cvt_pk_fp8_f32 v96, v182, v183
	v_cvt_pk_fp8_f32 v97, v186, v187
	v_mfma_scale_f32_32x32x64_f8f6f4 v[80:95], v[220:225], v[132:137], v[80:95], v162, v143 op_sel_hi:[0,0,0] cbsz:2 blgp:2
	ds_read_b128 v[214:217], v140 offset:34816
	ds_read_b128 v[218:221], v140 offset:35328
	v_cvt_pk_fp8_f32 v98, v190, v191
	v_cvt_pk_fp8_f32 v99, v194, v195
	v_cvt_pk_fp8_f32 v96, v184, v185 op_sel:[0,0,1]
	v_cvt_pk_fp8_f32 v97, v188, v189 op_sel:[0,0,1]
	v_cvt_pk_fp8_f32 v98, v192, v193 op_sel:[0,0,1]
	v_cvt_pk_fp8_f32 v99, v196, v197 op_sel:[0,0,1]
	v_cvt_pk_fp8_f32 v100, v198, v199
	v_cvt_pk_fp8_f32 v101, v202, v203
	v_cvt_pk_fp8_f32 v102, v206, v207
	v_cvt_pk_fp8_f32 v103, v210, v211
	v_cvt_pk_fp8_f32 v100, v200, v201 op_sel:[0,0,1]
	v_cvt_pk_fp8_f32 v101, v204, v205 op_sel:[0,0,1]
	v_cvt_pk_fp8_f32 v102, v208, v209 op_sel:[0,0,1]
	v_cvt_pk_fp8_f32 v103, v212, v213 op_sel:[0,0,1]
	s_waitcnt lgkmcnt(2)
	s_nop 0
	v_mfma_f32_32x32x64_f8f6f4 v[0:15], v[96:103], v[104:111], v[0:15]
	s_cmpk_gt_u32 s53, 0x101
	s_cbranch_scc1 .Lmask_last
	.Lmask_ret:
	v_max_f32_e32 v229, v64, v65
	v_max3_f32 v229, v229, v66, v67
	v_max3_f32 v229, v229, v68, v69
	v_max3_f32 v229, v229, v70, v71
	v_max3_f32 v229, v229, v72, v73
	v_max3_f32 v229, v229, v74, v75
	v_max3_f32 v229, v229, v76, v77
	v_max3_f32 v229, v229, v78, v79
	v_mfma_f32_32x32x64_f8f6f4 v[48:63], v[96:103], v[112:119], v[48:63]
	v_max3_f32 v229, v229, v80, v81
	v_max3_f32 v229, v229, v82, v83
	v_max3_f32 v229, v229, v84, v85
	v_max3_f32 v229, v229, v86, v87
	v_max3_f32 v229, v229, v88, v89
	v_max3_f32 v229, v229, v90, v91
	v_max3_f32 v229, v229, v92, v93
	v_max3_f32 v229, v229, v94, v95
	v_mov_b32_e32 v160, v229
	s_nop 1
	v_permlane32_swap_b32_e32 v229, v160
	v_max_f32_e32 v229, v229, v160
	v_cmp_ge_f32_e32 vcc, s69, v229
	s_cmp_eq_u64 vcc, exec
	v_mov_b32_e32 v228, 1.0
	s_cbranch_scc0 .Lslow_b1
	v_mfma_f32_32x32x64_f8f6f4 v[16:31], v[96:103], v[148:155], v[16:31]
	v_exp_f32_e32 v64, v64
	v_exp_f32_e32 v65, v65
	v_exp_f32_e32 v66, v66
	v_exp_f32_e32 v67, v67
	v_exp_f32_e32 v68, v68
	v_exp_f32_e32 v69, v69
	s_waitcnt lgkmcnt(0)
	v_mfma_f32_32x32x64_f8f6f4 v[32:47], v[96:103], v[214:221], v[32:47]
	v_exp_f32_e32 v70, v70
	v_exp_f32_e32 v71, v71
	v_exp_f32_e32 v72, v72
	v_exp_f32_e32 v73, v73
	v_exp_f32_e32 v74, v74
	v_exp_f32_e32 v75, v75
	v_mfma_f32_16x16x128_f8f6f4 v[144:147], v[232:239], v[96:103], 0
	v_exp_f32_e32 v76, v76
	v_exp_f32_e32 v77, v77
	v_exp_f32_e32 v78, v78
	v_exp_f32_e32 v79, v79
	s_waitcnt vmcnt(0)
	s_barrier

; DEVINL int crow(int r, int hi) { return (r & 3) + 8 * (r >> 2) + 4 * hi; }
; #define SBAR() __builtin_amdgcn_sched_barrier(0)
; #define PVM(db) do { const i32x8 b = {(int)f.v[db][0][0], (int)f.v[db][0][1], (int)f.v[db][0][2], (int)f.v[db][0][3], (int)f.v[db][1][0], (int)f.v[db][1][1], (int)f.v[db][1][2], (int)f.v[db][1][3]}; \
;     o[db] = MFMA8(pa, b, o[db]); } while (0)
; DEVINL void pv_psm(f32x16* o, const VFrag& f, const i32x8& pa, f32x16& lsum, const i32x8& ones8,
;                    f32x16& p0, f32x16& p1, float& m_reg, float& mn, float& alpha, int kvalid, int hi) {
;   constexpr float C = MLA_SCALE * 1.4426950408889634f;
;     ...
;   if (kvalid < 64) {
; #pragma unroll
;     for (int r = 0; r < 16; ++r) { if (crow(r, hi) >= kvalid) p0[r] = -1e30f; if (32 + crow(r, hi) >= kvalid) p1[r] = -1e30f; }
;   }
;   PVM(0);
;   float pmax = p0[0];
; #pragma unroll
;   for (int r = 1; r < 16; ++r) pmax = fmaxf(pmax, p0[r]);
;   SBAR();
;   PVM(1);
; #pragma unroll
;   for (int r = 0; r < 16; ++r) pmax = fmaxf(pmax, p1[r]);
;   { auto rr = __builtin_amdgcn_permlane32_swap(__float_as_uint(pmax), __float_as_uint(pmax), false, false);
;     pmax = fmaxf(__uint_as_float(rr[0]), __uint_as_float(rr[1])); }
;   SBAR();
;   PVM(2);
;   if (__builtin_expect(__all(pmax - m_reg <= THR / MLA_SCALE), 1)) { mn = m_reg; alpha = 1.f; }
;   else { mn = fmaxf(m_reg, pmax); alpha = __builtin_amdgcn_exp2f((m_reg - mn) * C); m_reg = mn; }
.Lslow_a0:
	v_mfma_f32_32x32x64_f8f6f4 v[16:31], v[96:103], v[148:155], v[16:31]
	s_waitcnt lgkmcnt(0)
	v_mfma_f32_32x32x64_f8f6f4 v[32:47], v[96:103], v[214:221], v[32:47]
	v_mfma_f32_16x16x128_f8f6f4 v[144:147], v[232:239], v[96:103], 0
	v_sub_f32_e32 v141, v229, v164
	v_max_f32_e32 v141, 0, v141
	v_exp_f32_e64 v226, -v141
	v_sub_f32_e32 v230, v230, v141
	v_mov_b32_e32 v240, v230
	v_mov_b32_e32 v241, v230
	v_mov_b32_e32 v242, v230
	v_mov_b32_e32 v243, v230
	v_mov_b32_e32 v244, v230
	v_mov_b32_e32 v245, v230
	v_mov_b32_e32 v246, v230
	v_mov_b32_e32 v247, v230
	v_mov_b32_e32 v248, v230
	v_mov_b32_e32 v249, v230
	v_mov_b32_e32 v250, v230
	v_mov_b32_e32 v251, v230
	v_mov_b32_e32 v252, v230
	v_mov_b32_e32 v253, v230
	v_mov_b32_e32 v254, v230
	v_mov_b32_e32 v255, v230
	v_sub_f32_e32 v182, v182, v141
	v_sub_f32_e32 v183, v183, v141
	v_sub_f32_e32 v184, v184, v141
	v_sub_f32_e32 v185, v185, v141
	v_sub_f32_e32 v186, v186, v141
	v_sub_f32_e32 v187, v187, v141
	v_sub_f32_e32 v188, v188, v141
	v_sub_f32_e32 v189, v189, v141
	v_sub_f32_e32 v190, v190, v141
	v_sub_f32_e32 v191, v191, v141
	v_sub_f32_e32 v192, v192, v141
	v_sub_f32_e32 v193, v193, v141
	v_sub_f32_e32 v194, v194, v141
	v_sub_f32_e32 v195, v195, v141
	v_sub_f32_e32 v196, v196, v141
	v_sub_f32_e32 v197, v197, v141
	v_sub_f32_e32 v198, v198, v141
	v_sub_f32_e32 v199, v199, v141
	v_sub_f32_e32 v200, v200, v141
	v_sub_f32_e32 v201, v201, v141
	v_sub_f32_e32 v202, v202, v141
	v_sub_f32_e32 v203, v203, v141
	v_sub_f32_e32 v204, v204, v141
	v_sub_f32_e32 v205, v205, v141
	v_sub_f32_e32 v206, v206, v141
	v_sub_f32_e32 v207, v207, v141
	v_sub_f32_e32 v208, v208, v141
	v_sub_f32_e32 v209, v209, v141
	v_sub_f32_e32 v210, v210, v141
	v_sub_f32_e32 v211, v211, v141
	v_sub_f32_e32 v212, v212, v141
	v_sub_f32_e32 v213, v213, v141
	s_and_saveexec_b64 s[16:17], s[6:7]
	ds_write_b32 v178, v226 offset:128
	s_or_b64 exec, exec, s[16:17]
	s_waitcnt lgkmcnt(0)
	v_add_u32_e32 v142, v171, v177
	ds_read_b128 v[104:107], v142 offset:224
	ds_read_b128 v[108:111], v142 offset:192
	ds_read_b128 v[112:115], v142 offset:160
	ds_read_b128 v[116:119], v142 offset:128
	s_waitcnt lgkmcnt(0)
	v_pk_mul_f32 v[12:13], v[12:13], v[104:105]
	v_pk_mul_f32 v[8:9], v[8:9], v[108:109]
	v_pk_mul_f32 v[4:5], v[4:5], v[112:113]
	v_pk_mul_f32 v[14:15], v[14:15], v[106:107]
	v_pk_mul_f32 v[10:11], v[10:11], v[110:111]
	v_pk_mul_f32 v[6:7], v[6:7], v[114:115]
	v_pk_mul_f32 v[2:3], v[2:3], v[118:119]
	v_pk_mul_f32 v[0:1], v[0:1], v[116:117]
	v_pk_mul_f32 v[60:61], v[60:61], v[104:105]
	v_pk_mul_f32 v[56:57], v[56:57], v[108:109]
	v_pk_mul_f32 v[52:53], v[52:53], v[112:113]
	v_pk_mul_f32 v[62:63], v[62:63], v[106:107]
	v_pk_mul_f32 v[58:59], v[58:59], v[110:111]
	v_pk_mul_f32 v[54:55], v[54:55], v[114:115]
	v_pk_mul_f32 v[50:51], v[50:51], v[118:119]
	v_pk_mul_f32 v[48:49], v[48:49], v[116:117]
	v_pk_mul_f32 v[28:29], v[28:29], v[104:105]
	v_pk_mul_f32 v[24:25], v[24:25], v[108:109]
	v_pk_mul_f32 v[20:21], v[20:21], v[112:113]
	v_pk_mul_f32 v[30:31], v[30:31], v[106:107]
	v_pk_mul_f32 v[26:27], v[26:27], v[110:111]
	v_pk_mul_f32 v[22:23], v[22:23], v[114:115]
	v_pk_mul_f32 v[18:19], v[18:19], v[118:119]
	v_pk_mul_f32 v[16:17], v[16:17], v[116:117]
	v_pk_mul_f32 v[44:45], v[44:45], v[104:105]
	v_pk_mul_f32 v[40:41], v[40:41], v[108:109]
	v_pk_mul_f32 v[36:37], v[36:37], v[112:113]
	v_pk_mul_f32 v[46:47], v[46:47], v[106:107]
	v_pk_mul_f32 v[42:43], v[42:43], v[110:111]
	v_pk_mul_f32 v[38:39], v[38:39], v[114:115]
	v_pk_mul_f32 v[34:35], v[34:35], v[118:119]
	v_pk_mul_f32 v[32:33], v[32:33], v[116:117]
	v_exp_f32_e32 v182, v182
	v_exp_f32_e32 v183, v183
	v_exp_f32_e32 v184, v184
	v_exp_f32_e32 v185, v185
	v_exp_f32_e32 v186, v186
	v_exp_f32_e32 v187, v187
	v_exp_f32_e32 v188, v188
	v_exp_f32_e32 v189, v189
	v_exp_f32_e32 v190, v190
	v_exp_f32_e32 v191, v191
	v_exp_f32_e32 v192, v192
	v_exp_f32_e32 v193, v193
	v_exp_f32_e32 v194, v194
	v_exp_f32_e32 v195, v195
	v_exp_f32_e32 v196, v196
	v_exp_f32_e32 v197, v197
	s_branch .Ljoin_a0
; DEVINL int crow(int r, int hi) { return (r & 3) + 8 * (r >> 2) + 4 * hi; }
; #define SBAR() __builtin_amdgcn_sched_barrier(0)
; #define PVM(db) do { const i32x8 b = {(int)f.v[db][0][0], (int)f.v[db][0][1], (int)f.v[db][0][2], (int)f.v[db][0][3], (int)f.v[db][1][0], (int)f.v[db][1][1], (int)f.v[db][1][2], (int)f.v[db][1][3]}; \
;     o[db] = MFMA8(pa, b, o[db]); } while (0)
; DEVINL void pv_psm(f32x16* o, const VFrag& f, const i32x8& pa, f32x16& lsum, const i32x8& ones8,
;                    f32x16& p0, f32x16& p1, float& m_reg, float& mn, float& alpha, int kvalid, int hi) {
;   constexpr float C = MLA_SCALE * 1.4426950408889634f;
;     ...
;   if (kvalid < 64) {
; #pragma unroll
;     for (int r = 0; r < 16; ++r) { if (crow(r, hi) >= kvalid) p0[r] = -1e30f; if (32 + crow(r, hi) >= kvalid) p1[r] = -1e30f; }
;   }
;   PVM(0);
;   float pmax = p0[0];
; #pragma unroll
;   for (int r = 1; r < 16; ++r) pmax = fmaxf(pmax, p0[r]);
;   SBAR();
;   PVM(1);
; #pragma unroll
;   for (int r = 0; r < 16; ++r) pmax = fmaxf(pmax, p1[r]);
;   { auto rr = __builtin_amdgcn_permlane32_swap(__float_as_uint(pmax), __float_as_uint(pmax), false, false);
;     pmax = fmaxf(__uint_as_float(rr[0]), __uint_as_float(rr[1])); }
;   SBAR();
;   PVM(2);
;   if (__builtin_expect(__all(pmax - m_reg <= THR / MLA_SCALE), 1)) { mn = m_reg; alpha = 1.f; }
;   else { mn = fmaxf(m_reg, pmax); alpha = __builtin_amdgcn_exp2f((m_reg - mn) * C); m_reg = mn; }
.Lslow_b0:
	v_mfma_f32_32x32x64_f8f6f4 v[16:31], v[96:103], v[148:155], v[16:31]
	s_waitcnt lgkmcnt(0)
	v_mfma_f32_32x32x64_f8f6f4 v[32:47], v[96:103], v[214:221], v[32:47]
	v_mfma_f32_16x16x128_f8f6f4 v[144:147], v[232:239], v[96:103], 0
	s_waitcnt vmcnt(0)
	s_barrier
	v_sub_f32_e32 v141, v229, v164
	v_max_f32_e32 v141, 0, v141
	v_exp_f32_e64 v228, -v141
	v_sub_f32_e32 v230, v230, v141
	v_mov_b32_e32 v240, v230
	v_mov_b32_e32 v241, v230
	v_mov_b32_e32 v242, v230
	v_mov_b32_e32 v243, v230
	v_mov_b32_e32 v244, v230
	v_mov_b32_e32 v245, v230
	v_mov_b32_e32 v246, v230
	v_mov_b32_e32 v247, v230
	v_mov_b32_e32 v248, v230
	v_mov_b32_e32 v249, v230
	v_mov_b32_e32 v250, v230
	v_mov_b32_e32 v251, v230
	v_mov_b32_e32 v252, v230
	v_mov_b32_e32 v253, v230
	v_mov_b32_e32 v254, v230
	v_mov_b32_e32 v255, v230
	v_sub_f32_e32 v64, v64, v141
	v_sub_f32_e32 v65, v65, v141
	v_sub_f32_e32 v66, v66, v141
	v_sub_f32_e32 v67, v67, v141
	v_sub_f32_e32 v68, v68, v141
	v_sub_f32_e32 v69, v69, v141
	v_sub_f32_e32 v70, v70, v141
	v_sub_f32_e32 v71, v71, v141
	v_sub_f32_e32 v72, v72, v141
	v_sub_f32_e32 v73, v73, v141
	v_sub_f32_e32 v74, v74, v141
	v_sub_f32_e32 v75, v75, v141
	v_sub_f32_e32 v76, v76, v141
	v_sub_f32_e32 v77, v77, v141
	v_sub_f32_e32 v78, v78, v141
	v_sub_f32_e32 v79, v79, v141
	v_sub_f32_e32 v80, v80, v141
	v_sub_f32_e32 v81, v81, v141
	v_sub_f32_e32 v82, v82, v141
	v_sub_f32_e32 v83, v83, v141
	v_sub_f32_e32 v84, v84, v141
	v_sub_f32_e32 v85, v85, v141
	v_sub_f32_e32 v86, v86, v141
	v_sub_f32_e32 v87, v87, v141
	v_sub_f32_e32 v88, v88, v141
	v_sub_f32_e32 v89, v89, v141
	v_sub_f32_e32 v90, v90, v141
	v_sub_f32_e32 v91, v91, v141
	v_sub_f32_e32 v92, v92, v141
	v_sub_f32_e32 v93, v93, v141
	v_sub_f32_e32 v94, v94, v141
	v_sub_f32_e32 v95, v95, v141
	s_and_saveexec_b64 s[16:17], s[6:7]
	ds_write_b32 v178, v228 offset:128
	s_or_b64 exec, exec, s[16:17]
	s_waitcnt lgkmcnt(0)
	v_add_u32_e32 v142, v171, v177
	ds_read_b128 v[104:107], v142 offset:224
	ds_read_b128 v[108:111], v142 offset:192
	ds_read_b128 v[112:115], v142 offset:160
	ds_read_b128 v[116:119], v142 offset:128
	s_waitcnt lgkmcnt(0)
	v_pk_mul_f32 v[12:13], v[12:13], v[104:105]
	v_pk_mul_f32 v[8:9], v[8:9], v[108:109]
	v_pk_mul_f32 v[4:5], v[4:5], v[112:113]
	v_pk_mul_f32 v[14:15], v[14:15], v[106:107]
	v_pk_mul_f32 v[10:11], v[10:11], v[110:111]
	v_pk_mul_f32 v[6:7], v[6:7], v[114:115]
	v_pk_mul_f32 v[2:3], v[2:3], v[118:119]
	v_pk_mul_f32 v[0:1], v[0:1], v[116:117]
	v_pk_mul_f32 v[60:61], v[60:61], v[104:105]
	v_pk_mul_f32 v[56:57], v[56:57], v[108:109]
	v_pk_mul_f32 v[52:53], v[52:53], v[112:113]
	v_pk_mul_f32 v[62:63], v[62:63], v[106:107]
	v_pk_mul_f32 v[58:59], v[58:59], v[110:111]
	v_pk_mul_f32 v[54:55], v[54:55], v[114:115]
	v_pk_mul_f32 v[50:51], v[50:51], v[118:119]
	v_pk_mul_f32 v[48:49], v[48:49], v[116:117]
	v_pk_mul_f32 v[28:29], v[28:29], v[104:105]
	v_pk_mul_f32 v[24:25], v[24:25], v[108:109]
	v_pk_mul_f32 v[20:21], v[20:21], v[112:113]
	v_pk_mul_f32 v[30:31], v[30:31], v[106:107]
	v_pk_mul_f32 v[26:27], v[26:27], v[110:111]
	v_pk_mul_f32 v[22:23], v[22:23], v[114:115]
	v_pk_mul_f32 v[18:19], v[18:19], v[118:119]
	v_pk_mul_f32 v[16:17], v[16:17], v[116:117]
	v_pk_mul_f32 v[44:45], v[44:45], v[104:105]
	v_pk_mul_f32 v[40:41], v[40:41], v[108:109]
	v_pk_mul_f32 v[36:37], v[36:37], v[112:113]
	v_pk_mul_f32 v[46:47], v[46:47], v[106:107]
	v_pk_mul_f32 v[42:43], v[42:43], v[110:111]
	v_pk_mul_f32 v[38:39], v[38:39], v[114:115]
	v_pk_mul_f32 v[34:35], v[34:35], v[118:119]
	v_pk_mul_f32 v[32:33], v[32:33], v[116:117]
	v_exp_f32_e32 v64, v64
	v_exp_f32_e32 v65, v65
	v_exp_f32_e32 v66, v66
	v_exp_f32_e32 v67, v67
	v_exp_f32_e32 v68, v68
	v_exp_f32_e32 v69, v69
	v_exp_f32_e32 v70, v70
	v_exp_f32_e32 v71, v71
	v_exp_f32_e32 v72, v72
	v_exp_f32_e32 v73, v73
	v_exp_f32_e32 v74, v74
	v_exp_f32_e32 v75, v75
	v_exp_f32_e32 v76, v76
	v_exp_f32_e32 v77, v77
	v_exp_f32_e32 v78, v78
	v_exp_f32_e32 v79, v79
	s_branch .Ljoin_b0
